# N2/N3 norm rows walked in descending order so the sample rows (12 serialized partial-sum loads) overlap with other rows instead of forming a tail
# speedup vs baseline: 1.0059x; 1.0010x over previous
; __device__ __forceinline__ void phase_norm_mid(const Params& P, int l, int gw, int NGW, int lane) {
;     bf16_t* H = (bf16_t*)(P.ws + WS_H); const float* O = (const float*)(P.ws + WS_GATES); float* X1 = (float*)(P.ws + WS_X1);
;     const float* gp = P.g_mix_post + (size_t)l * DM;
;     for (int r = gw; r < MROWS; r += NGW) {
;         f32x4 o[8], x[8];
;         if (r < TP) row_load(O + (size_t)r * DM, lane, o);
.LBB0_882:
	s_waitcnt lgkmcnt(0)
	s_barrier
	v_mbcnt_lo_u32_b32 v0, -1, 0
	v_mbcnt_hi_u32_b32 v0, -1, v0
	v_readlane_b32 s0, v252, 32
	v_or_b32_e32 v2, s85, v0
	v_readlane_b32 s1, v252, 33
	v_ashrrev_i32_e32 v0, 6, v2
	v_add_u32_e32 v1, s0, v0
	s_lshl_b32 s0, s96, 11
	s_mov_b32 s1, s83
	v_writelane_b32 v255, s0, 2
	s_nop 1
	v_writelane_b32 v255, s1, 3
	s_movk_i32 s0, 0x2080
	v_cmp_gt_i32_e32 vcc, s0, v1
	s_and_saveexec_b64 s[0:1], vcc
	s_cbranch_execz .LBB0_895
	v_lshlrev_b32_e32 v1, 2, v2
	v_and_b32_e32 v4, 0xfc, v1
	v_and_b32_e32 v1, 64, v246
	v_add_u32_e32 v1, 64, v1
	v_xor_b32_e32 v3, 1, v246
	v_cmp_lt_i32_e32 vcc, v3, v1
	v_readlane_b32 s2, v255, 2
	v_readlane_b32 s3, v255, 3
	v_cndmask_b32_e32 v3, v246, v3, vcc
	v_lshlrev_b32_e32 v100, 2, v3
	v_xor_b32_e32 v3, 2, v246
	v_cmp_lt_i32_e32 vcc, v3, v1
	s_lshl_b64 s[2:3], s[2:3], 2
	s_add_u32 s4, s56, s2
	v_cndmask_b32_e32 v3, v246, v3, vcc
	v_lshlrev_b32_e32 v101, 2, v3
	v_xor_b32_e32 v3, 4, v246
	v_cmp_lt_i32_e32 vcc, v3, v1
	s_addc_u32 s5, s57, s3
	v_lshlrev_b32_e32 v8, 2, v4
	v_cndmask_b32_e32 v3, v246, v3, vcc
	v_lshlrev_b32_e32 v102, 2, v3
	v_xor_b32_e32 v3, 8, v246
	v_cmp_lt_i32_e32 vcc, v3, v1
	s_add_u32 s2, s58, s2
	v_lshl_add_u64 v[50:51], s[4:5], 0, v[8:9]
	v_cndmask_b32_e32 v3, v246, v3, vcc
	v_lshlrev_b32_e32 v103, 2, v3
	v_xor_b32_e32 v3, 16, v246
	v_cmp_lt_i32_e32 vcc, v3, v1
	v_readlane_b32 s4, v254, 22
	s_addc_u32 s3, s59, s3
	v_cndmask_b32_e32 v3, v246, v3, vcc
	v_lshlrev_b32_e32 v104, 2, v3
	v_xor_b32_e32 v3, 32, v246
	v_cmp_lt_i32_e32 vcc, v3, v1
	v_readlane_b32 s5, v254, 23
	v_lshl_add_u64 v[66:67], s[2:3], 0, v[8:9]
	v_cndmask_b32_e32 v1, v246, v3, vcc
	v_readlane_b32 s2, v252, 32
	v_lshlrev_b32_e32 v105, 2, v1
	v_lshl_add_u64 v[52:53], s[4:5], 0, v[8:9]
	v_readlane_b32 s4, v252, 58
	v_ashrrev_i32_e32 v1, 31, v0
	v_readlane_b32 s3, v252, 33
	v_lshlrev_b32_e32 v6, 1, v4
	v_mov_b32_e32 v7, v9
	v_readlane_b32 s5, v252, 59
	v_lshl_add_u64 v[76:77], s[2:3], 0, v[0:1]
	s_nop 0
	v_readfirstlane_b32 s8, v76
.Lrev_n2_loop:
	s_add_u32 s9, s8, s74
	s_cmp_le_u32 s9, 0x207f
	s_cbranch_scc0 .Lrev_n2_done
	s_mov_b32 s8, s9
	s_branch .Lrev_n2_loop
.Lrev_n2_done:
	v_mov_b32_e32 v76, s8
	v_lshlrev_b64 v[0:1], 13, v[76:77]
	v_lshl_add_u64 v[54:55], s[4:5], 0, v[6:7]
	v_readlane_b32 s4, v254, 34
	v_and_b32_e32 v2, 63, v2
	v_readlane_b32 s2, v252, 62
	s_mov_b64 s[8:9], 0x1000
	s_mov_b64 s[14:15], 0x1400
	s_mov_b64 s[18:19], 0x1800
	s_mov_b64 s[20:21], 0x1c00
	v_readlane_b32 s5, v254, 35
	v_lshl_or_b32 v0, v2, 4, v0
	v_readlane_b32 s3, v252, 63
	v_lshl_add_u64 v[56:57], v[50:51], 0, s[8:9]
	v_lshl_add_u64 v[58:59], v[50:51], 0, s[14:15]
	v_lshl_add_u64 v[60:61], v[50:51], 0, s[18:19]
	v_lshl_add_u64 v[62:63], v[50:51], 0, s[20:21]
	v_lshl_add_u64 v[64:65], s[4:5], 0, v[8:9]
	v_lshl_add_u64 v[68:69], v[66:67], 0, s[8:9]
	v_lshl_add_u64 v[70:71], v[66:67], 0, s[14:15]
	v_lshl_add_u64 v[72:73], v[66:67], 0, s[18:19]
	v_lshl_add_u64 v[74:75], v[66:67], 0, s[20:21]
	v_lshl_add_u64 v[78:79], s[2:3], 0, v[0:1]
	s_mov_b64 s[2:3], 0
	v_lshlrev_b32_e32 v8, 2, v4
	global_load_dwordx4 v[124:127], v[50:51], off
	global_load_dwordx4 v[128:131], v[50:51], off offset:1024
	global_load_dwordx4 v[132:135], v[50:51], off offset:2048
	global_load_dwordx4 v[136:139], v[50:51], off offset:3072
	global_load_dwordx4 v[140:143], v[56:57], off
	global_load_dwordx4 v[144:147], v[58:59], off
	global_load_dwordx4 v[148:151], v[60:61], off
	global_load_dwordx4 v[152:155], v[62:63], off
	global_load_dwordx4 v[156:159], v[66:67], off
	global_load_dwordx4 v[160:163], v[66:67], off offset:1024
	global_load_dwordx4 v[164:167], v[66:67], off offset:2048
	global_load_dwordx4 v[168:171], v[66:67], off offset:3072
	global_load_dwordx4 v[172:175], v[68:69], off
	global_load_dwordx4 v[176:179], v[70:71], off
	global_load_dwordx4 v[180:183], v[72:73], off
	global_load_dwordx4 v[184:187], v[74:75], off
	s_branch .LBB0_886

; __device__ __forceinline__ void phase_norm_mid(const Params& P, int l, int gw, int NGW, int lane) {
;     ...
;     for (int r = gw; r < MROWS; r += NGW) {
;         f32x4 o[8], x[8];
;         if (r < TP) row_load(O + (size_t)r * DM, lane, o);
;         else { const float* sr = (const float*)(P.ws + WS_SROW) + (size_t)(r - TP) * DM; row_load(sr, lane, o);
; #pragma unroll
;             for (int p = 1; p < 12; ++p) { f32x4 t[8]; row_load(sr + (size_t)p * 128 * DM, lane, t);
; #pragma unroll
;                 for (int j = 0; j < 8; ++j) o[j] = o[j] + t[j]; } }
;         row_load(layer_in_row(P, l, r), lane, x);
;         __builtin_amdgcn_sched_barrier(0);
;         const float rs = row_rstd(o);
; #pragma unroll
;         for (int j = 0; j < 8; ++j) { const f32x4 gg = *(const f32x4*)(gp + 4 * lane + 256 * j); x[j] = x[j] + o[j] * rs * gg; *(f32x4*)(X1 + (size_t)r * DM + 4 * lane + 256 * j) = x[j]; }
.LBB0_885:
	v_lshlrev_b64 v[34:35], 13, v[34:35]
	v_lshl_add_u64 v[34:35], v[36:37], 0, v[34:35]
	v_lshl_add_u64 v[34:35], v[34:35], 0, v[8:9]
	global_load_dwordx4 v[82:85], v[34:35], off
	global_load_dwordx4 v[86:89], v[34:35], off offset:1024
	global_load_dwordx4 v[90:93], v[34:35], off offset:2048
	global_load_dwordx4 v[94:97], v[34:35], off offset:3072
	v_add_co_u32_e32 v34, vcc, 0x1000, v34
	s_nop 1
	v_addc_co_u32_e32 v35, vcc, 0, v35, vcc
	global_load_dwordx4 v[46:49], v[34:35], off
	global_load_dwordx4 v[42:45], v[34:35], off offset:1024
	global_load_dwordx4 v[38:41], v[34:35], off offset:2048
	s_nop 0
	global_load_dwordx4 v[34:37], v[34:35], off offset:3072
	s_waitcnt vmcnt(15)
	v_pk_mul_f32 v[116:117], v[30:31], v[30:31]
	s_waitcnt vmcnt(14)
	v_pk_mul_f32 v[118:119], v[26:27], v[26:27]
	v_pk_mul_f32 v[106:107], v[32:33], v[32:33]
	v_pk_mul_f32 v[108:109], v[28:29], v[28:29]
	v_mov_b32_e32 v120, v116
	v_mov_b32_e32 v121, v118
	v_mov_b32_e32 v118, v117
	v_pk_add_f32 v[116:117], v[120:121], v[118:119]
	v_mov_b32_e32 v118, v106
	v_mov_b32_e32 v119, v108
	v_mov_b32_e32 v108, v107
	v_pk_add_f32 v[106:107], v[118:119], v[108:109]
	s_waitcnt vmcnt(13)
	v_pk_mul_f32 v[112:113], v[24:25], v[24:25]
	v_pk_add_f32 v[106:107], v[116:117], v[106:107]
	v_pk_mul_f32 v[114:115], v[22:23], v[22:23]
	v_pk_add_f32 v[116:117], v[106:107], v[106:107] op_sel_hi:[0,1]
	v_pk_mov_b32 v[118:119], v[114:115], v[112:113] op_sel:[1,0]
	v_mov_b32_e32 v115, v113
	v_pk_add_f32 v[112:113], v[118:119], v[114:115]
	s_waitcnt vmcnt(11)
	v_mul_f32_e32 v116, v17, v17
	v_pk_add_f32 v[112:113], v[112:113], v[112:113] op_sel_hi:[0,1]
	v_mul_f32_e32 v112, v18, v18
	v_pk_fma_f32 v[114:115], v[18:19], v[18:19], v[112:113] op_sel_hi:[1,1,0]
	v_mul_f32_e32 v112, v20, v20
	v_pk_fma_f32 v[118:119], v[20:21], v[20:21], v[112:113] op_sel_hi:[1,1,0]
	v_mul_f32_e32 v114, v14, v14
	v_mul_f32_e32 v118, v15, v15
	v_mul_f32_e32 v112, v16, v16
	s_waitcnt vmcnt(10)
	v_pk_mul_f32 v[98:99], v[12:13], v[12:13]
	v_pk_mul_f32 v[110:111], v[10:11], v[10:11]
	v_pk_add_f32 v[114:115], v[114:115], v[118:119]
	v_pk_add_f32 v[112:113], v[112:113], v[116:117]
	s_movk_i32 s4, 0x1000
	v_pk_add_f32 v[112:113], v[114:115], v[112:113]
	v_pk_mov_b32 v[114:115], v[110:111], v[98:99] op_sel:[1,0]
	v_mov_b32_e32 v111, v99
	v_pk_add_f32 v[98:99], v[114:115], v[110:111]
	v_pk_add_f32 v[112:113], v[112:113], v[112:113] op_sel_hi:[0,1]
	v_pk_add_f32 v[98:99], v[98:99], v[98:99] op_sel_hi:[0,1]
	s_waitcnt vmcnt(9)
	v_mul_f32_e32 v98, v4, v4
	v_pk_fma_f32 v[110:111], v[4:5], v[4:5], v[98:99] op_sel_hi:[1,1,0]
	v_mul_f32_e32 v98, v6, v6
	v_pk_fma_f32 v[114:115], v[6:7], v[6:7], v[98:99] op_sel_hi:[1,1,0]
	s_waitcnt vmcnt(8)
	v_mul_f32_e32 v110, v0, v0
	v_mul_f32_e32 v114, v1, v1
	v_mul_f32_e32 v98, v2, v2
	v_mul_f32_e32 v112, v3, v3
	v_pk_add_f32 v[110:111], v[110:111], v[114:115]
	v_pk_add_f32 v[98:99], v[98:99], v[112:113]
	v_subrev_u32_e32 v76, s74, v76
	v_pk_add_f32 v[98:99], v[110:111], v[98:99]
	s_nop 0
	v_add_f32_e32 v98, v98, v99
	ds_bpermute_b32 v99, v100, v98
	s_waitcnt lgkmcnt(0)
	v_add_f32_e32 v98, v98, v99
	ds_bpermute_b32 v99, v101, v98
	s_waitcnt lgkmcnt(0)
	v_add_f32_e32 v98, v98, v99
	ds_bpermute_b32 v99, v102, v98
	s_waitcnt lgkmcnt(0)
	v_add_f32_e32 v98, v98, v99
	ds_bpermute_b32 v99, v103, v98
	s_waitcnt lgkmcnt(0)
	v_add_f32_e32 v98, v98, v99
	ds_bpermute_b32 v99, v104, v98
	s_waitcnt lgkmcnt(0)
	v_add_f32_e32 v98, v98, v99
	ds_bpermute_b32 v99, v105, v98
	s_waitcnt lgkmcnt(0)
	v_add_f32_e32 v98, v98, v99
	v_fmamk_f32 v98, v98, 0x3a000000, v240
	v_mul_f32_e32 v99, 0x4b800000, v98
	v_cmp_gt_f32_e32 vcc, s72, v98
	s_nop 1
	v_cndmask_b32_e32 v98, v98, v99, vcc
	v_rsq_f32_e32 v110, v98
	v_lshlrev_b64 v[98:99], 13, v[80:81]
	v_lshl_add_u64 v[98:99], v[52:53], 0, v[98:99]
	v_mul_f32_e32 v111, 0x45800000, v110
	v_cndmask_b32_e32 v110, v110, v111, vcc
	v_pk_mul_f32 v[30:31], v[30:31], v[110:111] op_sel_hi:[1,0]
	v_pk_mul_f32 v[32:33], v[32:33], v[110:111] op_sel_hi:[1,0]
	s_waitcnt vmcnt(0)
	v_pk_fma_f32 v[30:31], v[124:125], v[30:31], v[82:83]
	v_pk_fma_f32 v[32:33], v[126:127], v[32:33], v[84:85]
	global_store_dwordx4 v[98:99], v[30:33], off
	v_pk_mul_f32 v[26:27], v[26:27], v[110:111] op_sel_hi:[1,0]
	v_pk_mul_f32 v[28:29], v[28:29], v[110:111] op_sel_hi:[1,0]
	v_pk_mul_f32 v[22:23], v[22:23], v[110:111] op_sel_hi:[1,0]
	v_pk_mul_f32 v[24:25], v[24:25], v[110:111] op_sel_hi:[1,0]
	v_pk_mul_f32 v[18:19], v[18:19], v[110:111] op_sel_hi:[1,0]
	v_pk_mul_f32 v[20:21], v[20:21], v[110:111] op_sel_hi:[1,0]
	v_pk_mul_f32 v[14:15], v[14:15], v[110:111] op_sel_hi:[1,0]
	v_pk_mul_f32 v[16:17], v[16:17], v[110:111] op_sel_hi:[1,0]
	v_pk_mul_f32 v[10:11], v[10:11], v[110:111] op_sel_hi:[1,0]
	v_pk_mul_f32 v[12:13], v[12:13], v[110:111] op_sel_hi:[1,0]
	v_pk_mul_f32 v[4:5], v[4:5], v[110:111] op_sel_hi:[1,0]
	v_pk_mul_f32 v[6:7], v[6:7], v[110:111] op_sel_hi:[1,0]
	v_pk_mul_f32 v[0:1], v[0:1], v[110:111] op_sel_hi:[1,0]
	v_pk_mul_f32 v[2:3], v[2:3], v[110:111] op_sel_hi:[1,0]
	v_pk_fma_f32 v[28:29], v[130:131], v[28:29], v[88:89]
	v_pk_fma_f32 v[26:27], v[128:129], v[26:27], v[86:87]
	global_store_dwordx4 v[98:99], v[26:29], off offset:1024
	v_add_co_u32_e32 v86, vcc, s4, v98
	s_movk_i32 s4, 0x207f
	s_nop 0
	v_addc_co_u32_e32 v87, vcc, 0, v99, vcc
	v_pk_fma_f32 v[24:25], v[134:135], v[24:25], v[92:93]
	v_pk_fma_f32 v[22:23], v[132:133], v[22:23], v[90:91]
	global_store_dwordx4 v[98:99], v[22:25], off offset:2048
	v_pk_fma_f32 v[20:21], v[138:139], v[20:21], v[96:97]
	v_pk_fma_f32 v[18:19], v[136:137], v[18:19], v[94:95]
	global_store_dwordx4 v[98:99], v[18:21], off offset:3072
	v_pk_fma_f32 v[16:17], v[142:143], v[16:17], v[48:49]
; __device__ __forceinline__ void phase_norm_mid(const Params& P, int l, int gw, int NGW, int lane) {
;     ...
;     for (int r = gw; r < MROWS; r += NGW) {
;         f32x4 o[8], x[8];
;         if (r < TP) row_load(O + (size_t)r * DM, lane, o);
;         else { const float* sr = (const float*)(P.ws + WS_SROW) + (size_t)(r - TP) * DM; row_load(sr, lane, o);
; #pragma unroll
;             for (int p = 1; p < 12; ++p) { f32x4 t[8]; row_load(sr + (size_t)p * 128 * DM, lane, t);
; #pragma unroll
;                 for (int j = 0; j < 8; ++j) o[j] = o[j] + t[j]; } }
;         row_load(layer_in_row(P, l, r), lane, x);
;         __builtin_amdgcn_sched_barrier(0);
;         const float rs = row_rstd(o);
; #pragma unroll
;         for (int j = 0; j < 8; ++j) { const f32x4 gg = *(const f32x4*)(gp + 4 * lane + 256 * j); x[j] = x[j] + o[j] * rs * gg; *(f32x4*)(X1 + (size_t)r * DM + 4 * lane + 256 * j) = x[j]; }
;         const float rs2 = row_rstd(x); row_store_bf16(H + (size_t)r * DM, lane, x, rs2, P.g_ffn_pre + (size_t)l * DM);
	v_pk_fma_f32 v[14:15], v[140:141], v[14:15], v[46:47]
	global_store_dwordx4 v[86:87], v[14:17], off
	v_pk_fma_f32 v[12:13], v[146:147], v[12:13], v[44:45]
	v_pk_fma_f32 v[10:11], v[144:145], v[10:11], v[42:43]
	global_store_dwordx4 v[86:87], v[10:13], off offset:1024
	v_mov_b32_e32 v48, v33
	v_mov_b32_e32 v49, v29
	v_mov_b32_e32 v46, v32
	v_mov_b32_e32 v47, v28
	v_pk_mul_f32 v[48:49], v[48:49], v[48:49]
	v_pk_fma_f32 v[6:7], v[6:7], v[150:151], v[40:41]
	v_pk_fma_f32 v[4:5], v[4:5], v[148:149], v[38:39]
	global_store_dwordx4 v[86:87], v[4:7], off offset:2048
	v_mov_b32_e32 v44, v31
	v_mov_b32_e32 v45, v27
	v_mov_b32_e32 v42, v30
	v_mov_b32_e32 v43, v26
	v_pk_mul_f32 v[44:45], v[44:45], v[44:45]
	v_pk_fma_f32 v[2:3], v[2:3], v[154:155], v[36:37]
	v_pk_fma_f32 v[0:1], v[0:1], v[152:153], v[34:35]
	global_store_dwordx4 v[86:87], v[0:3], off offset:3072
	v_pk_fma_f32 v[42:43], v[42:43], v[42:43], v[44:45]
	v_pk_fma_f32 v[44:45], v[46:47], v[46:47], v[48:49]
	v_pk_mul_f32 v[46:47], v[24:25], v[24:25]
	v_pk_add_f32 v[42:43], v[42:43], v[44:45]
	v_pk_mul_f32 v[44:45], v[22:23], v[22:23]
	v_pk_add_f32 v[42:43], v[42:43], v[42:43] op_sel_hi:[0,1]
	v_pk_mov_b32 v[48:49], v[44:45], v[46:47] op_sel:[1,0]
	v_mov_b32_e32 v45, v47
	v_pk_add_f32 v[44:45], v[48:49], v[44:45]
	v_mul_f32_e32 v42, v18, v18
	v_mul_f32_e32 v38, v20, v20
	v_pk_add_f32 v[44:45], v[44:45], v[44:45] op_sel_hi:[0,1]
	v_pk_fma_f32 v[40:41], v[18:19], v[18:19], v[42:43] op_sel_hi:[1,1,0]
	v_pk_fma_f32 v[38:39], v[20:21], v[20:21], v[38:39] op_sel_hi:[1,1,0]
	v_mul_f32_e32 v40, v14, v14
	v_mul_f32_e32 v38, v15, v15
	v_mul_f32_e32 v44, v16, v16
	v_mul_f32_e32 v42, v17, v17
	v_pk_add_f32 v[38:39], v[40:41], v[38:39]
	v_pk_add_f32 v[40:41], v[44:45], v[42:43]
	v_pk_mul_f32 v[42:43], v[12:13], v[12:13]
	v_pk_add_f32 v[38:39], v[38:39], v[40:41]
	v_pk_mul_f32 v[40:41], v[10:11], v[10:11]
	v_pk_add_f32 v[38:39], v[38:39], v[38:39] op_sel_hi:[0,1]
	v_pk_mov_b32 v[44:45], v[40:41], v[42:43] op_sel:[1,0]
	v_mov_b32_e32 v41, v43
	v_pk_add_f32 v[40:41], v[44:45], v[40:41]
	v_mul_f32_e32 v38, v4, v4
	v_pk_add_f32 v[40:41], v[40:41], v[40:41] op_sel_hi:[0,1]
	v_mul_f32_e32 v40, v6, v6
	v_pk_fma_f32 v[42:43], v[4:5], v[4:5], v[38:39] op_sel_hi:[1,1,0]
	v_pk_fma_f32 v[44:45], v[6:7], v[6:7], v[40:41] op_sel_hi:[1,1,0]
	v_mul_f32_e32 v42, v0, v0
	v_mul_f32_e32 v44, v1, v1
	v_mul_f32_e32 v40, v2, v2
	v_mul_f32_e32 v38, v3, v3
	v_pk_add_f32 v[42:43], v[42:43], v[44:45]
	v_pk_add_f32 v[38:39], v[40:41], v[38:39]
	s_nop 0
	v_pk_add_f32 v[38:39], v[42:43], v[38:39]
	s_nop 0
	v_add_f32_e32 v38, v38, v39
	ds_bpermute_b32 v39, v100, v38
	s_waitcnt lgkmcnt(0)
	v_add_f32_e32 v38, v38, v39
	ds_bpermute_b32 v39, v101, v38
	s_waitcnt lgkmcnt(0)
	v_add_f32_e32 v38, v38, v39
	ds_bpermute_b32 v39, v102, v38
	s_waitcnt lgkmcnt(0)
	v_add_f32_e32 v38, v38, v39
	ds_bpermute_b32 v39, v103, v38
	s_waitcnt lgkmcnt(0)
	v_add_f32_e32 v38, v38, v39
	ds_bpermute_b32 v39, v104, v38
	s_waitcnt lgkmcnt(0)
	v_add_f32_e32 v38, v38, v39
	ds_bpermute_b32 v39, v105, v38
	s_waitcnt lgkmcnt(0)
	v_add_f32_e32 v38, v38, v39
	v_fmamk_f32 v38, v38, 0x3a000000, v240
	v_mul_f32_e32 v39, 0x4b800000, v38
	v_cmp_gt_f32_e32 vcc, s72, v38
	s_nop 1
	v_cndmask_b32_e32 v38, v38, v39, vcc
	v_rsq_f32_e32 v40, v38
	v_lshlrev_b64 v[38:39], 12, v[80:81]
	v_lshl_add_u64 v[38:39], v[54:55], 0, v[38:39]
	v_mul_f32_e32 v41, 0x45800000, v40
	v_cndmask_b32_e32 v40, v40, v41, vcc
	v_mul_f32_e32 v30, v30, v40
	v_mul_f32_e32 v31, v31, v40
	v_mul_f32_e32 v32, v32, v40
	v_mul_f32_e32 v33, v33, v40
	v_mul_f32_e32 v30, v156, v30
	v_mul_f32_e32 v31, v157, v31
	v_mul_f32_e32 v32, v158, v32
	v_mul_f32_e32 v33, v159, v33
	v_cvt_pk_bf16_f32 v30, v30, v31
	v_cvt_pk_bf16_f32 v31, v32, v33
	global_store_dwordx2 v[38:39], v[30:31], off
	v_mul_f32_e32 v26, v26, v40
	v_mul_f32_e32 v27, v27, v40
	v_mul_f32_e32 v28, v28, v40
	v_mul_f32_e32 v29, v29, v40
	v_mul_f32_e32 v22, v22, v40
	v_mul_f32_e32 v23, v23, v40
	v_mul_f32_e32 v24, v24, v40
	v_mul_f32_e32 v25, v25, v40
	v_mul_f32_e32 v18, v18, v40
	v_mul_f32_e32 v19, v19, v40
	v_mul_f32_e32 v20, v20, v40
	v_mul_f32_e32 v21, v21, v40
	v_mul_f32_e32 v14, v14, v40
	v_mul_f32_e32 v15, v15, v40
	v_mul_f32_e32 v16, v16, v40
	v_mul_f32_e32 v17, v17, v40
	v_mul_f32_e32 v10, v10, v40
	v_mul_f32_e32 v11, v11, v40
	v_mul_f32_e32 v12, v12, v40
	v_mul_f32_e32 v13, v13, v40
	v_mul_f32_e32 v4, v4, v40
	v_mul_f32_e32 v5, v5, v40
	v_mul_f32_e32 v6, v6, v40
	v_mul_f32_e32 v7, v7, v40
	v_cmp_gt_i32_e32 vcc, 0, v76
	v_readlane_b32 s4, v254, 53
	v_mul_f32_e32 v0, v0, v40
	v_mul_f32_e32 v1, v1, v40
	v_readlane_b32 s5, v254, 54
	s_sub_u32 s4, 0, s4
	s_subb_u32 s5, 0, s5
	s_or_b64 s[2:3], vcc, s[2:3]
	v_mul_f32_e32 v2, v2, v40
	v_mul_f32_e32 v3, v3, v40
	v_lshl_add_u64 v[78:79], v[78:79], 0, s[4:5]
	v_mul_f32_e32 v26, v160, v26
	v_mul_f32_e32 v27, v161, v27
	v_mul_f32_e32 v28, v162, v28
	v_mul_f32_e32 v29, v163, v29
	v_cvt_pk_bf16_f32 v26, v26, v27
	v_cvt_pk_bf16_f32 v27, v28, v29
	global_store_dwordx2 v[38:39], v[26:27], off offset:512
	v_mul_f32_e32 v22, v164, v22
	v_mul_f32_e32 v23, v165, v23
	v_mul_f32_e32 v24, v166, v24
	v_mul_f32_e32 v25, v167, v25
	v_cvt_pk_bf16_f32 v22, v22, v23
	v_cvt_pk_bf16_f32 v23, v24, v25
	global_store_dwordx2 v[38:39], v[22:23], off offset:1024
	v_mul_f32_e32 v18, v168, v18
	v_mul_f32_e32 v19, v169, v19
	v_mul_f32_e32 v20, v170, v20
	v_mul_f32_e32 v21, v171, v21
	v_cvt_pk_bf16_f32 v18, v18, v19
	v_cvt_pk_bf16_f32 v19, v20, v21
	global_store_dwordx2 v[38:39], v[18:19], off offset:1536
	v_mul_f32_e32 v14, v14, v172
	v_mul_f32_e32 v15, v15, v173
	v_mul_f32_e32 v16, v16, v174
	v_mul_f32_e32 v17, v17, v175
	v_cvt_pk_bf16_f32 v14, v14, v15
	v_cvt_pk_bf16_f32 v15, v16, v17
	global_store_dwordx2 v[38:39], v[14:15], off offset:2048
	v_mul_f32_e32 v10, v10, v176
	v_mul_f32_e32 v11, v11, v177
	v_mul_f32_e32 v12, v12, v178
	v_mul_f32_e32 v13, v13, v179
	v_cvt_pk_bf16_f32 v10, v10, v11
	v_cvt_pk_bf16_f32 v11, v12, v13
	global_store_dwordx2 v[38:39], v[10:11], off offset:2560
	v_mul_f32_e32 v4, v4, v180
	v_mul_f32_e32 v5, v5, v181
	v_mul_f32_e32 v6, v6, v182
	v_mul_f32_e32 v7, v7, v183
	v_cvt_pk_bf16_f32 v4, v4, v5
	v_cvt_pk_bf16_f32 v5, v6, v7
	global_store_dwordx2 v[38:39], v[4:5], off offset:3072
	v_mul_f32_e32 v0, v0, v184
	v_mul_f32_e32 v1, v1, v185
	v_mul_f32_e32 v2, v2, v186
	v_mul_f32_e32 v3, v3, v187
	v_cvt_pk_bf16_f32 v0, v0, v1
	v_cvt_pk_bf16_f32 v1, v2, v3
	global_store_dwordx2 v[38:39], v[0:1], off offset:3584
	s_andn2_b64 exec, exec, s[2:3]
	s_cbranch_execz .LBB0_895

; __device__ __forceinline__ void phase_norm_out(const Params& P, int l, int gw, int NGW, int lane) {
;     bf16_t* H = (bf16_t*)(P.ws + WS_H); const float* F = (const float*)(P.ws + WS_GATES); const float* X1 = (const float*)(P.ws + WS_X1);
;     float* dst = (l == 0) ? (float*)(P.ws + WS_X2) : P.out;
;     const float* gp = P.g_ffn_post + (size_t)l * DM;
;     for (int r = gw; r < MROWS; r += NGW) {
;         f32x4 f[8], x[8];
;         if (r < TP) row_load(F + (size_t)r * DM, lane, f);
;         else { const float* sr = (const float*)(P.ws + WS_SROW) + (size_t)(r - TP) * DM; row_load(sr, lane, f);
; #pragma unroll
;             for (int p = 1; p < 11; ++p) { f32x4 t[8]; row_load(sr + (size_t)p * 128 * DM, lane, t);
; #pragma unroll
;                 for (int j = 0; j < 8; ++j) f[j] = f[j] + t[j]; } }
;         row_load(X1 + (size_t)r * DM, lane, x);
;         __builtin_amdgcn_sched_barrier(0);
;         const float rs = row_rstd(f);
; #pragma unroll
;         for (int j = 0; j < 8; ++j) { const f32x4 gg = *(const f32x4*)(gp + 4 * lane + 256 * j); x[j] = x[j] + f[j] * rs * gg; *(f32x4*)(dst + (size_t)r * DM + 4 * lane + 256 * j) = x[j]; }
;         if (l == 0) { const float rs2 = row_rstd(x); row_store_bf16(H + (size_t)r * DM, lane, x, rs2, P.g_mix_pre + DM); }
.LBB0_2096:
	s_waitcnt lgkmcnt(0)
	s_barrier
	v_mbcnt_lo_u32_b32 v0, -1, 0
	v_mbcnt_hi_u32_b32 v0, -1, v0
	v_readlane_b32 s0, v252, 32
	v_or_b32_e32 v104, s85, v0
	v_readlane_b32 s1, v252, 33
	v_ashrrev_i32_e32 v50, 6, v104
	v_add_u32_e32 v102, s0, v50
	s_movk_i32 s0, 0x2080
	v_and_b32_e32 v103, 63, v104
	v_cmp_gt_i32_e32 vcc, s0, v102
	s_and_saveexec_b64 s[0:1], vcc
	s_cbranch_execz .LBB0_2105
	v_and_b32_e32 v0, 64, v246
	v_add_u32_e32 v0, 64, v0
	v_xor_b32_e32 v1, 1, v246
	v_cmp_lt_i32_e32 vcc, v1, v0
	v_readlane_b32 s2, v255, 2
	v_readlane_b32 s3, v255, 3
	v_cndmask_b32_e32 v1, v246, v1, vcc
	v_lshlrev_b32_e32 v105, 2, v1
	v_xor_b32_e32 v1, 2, v246
	v_cmp_lt_i32_e32 vcc, v1, v0
	s_lshl_b64 s[2:3], s[2:3], 2
	s_add_u32 s2, s60, s2
	v_cndmask_b32_e32 v1, v246, v1, vcc
	v_lshlrev_b32_e32 v106, 2, v1
	v_xor_b32_e32 v1, 4, v246
	v_cmp_lt_i32_e32 vcc, v1, v0
	s_addc_u32 s3, s61, s3
	v_lshlrev_b32_e32 v8, 4, v103
	v_cndmask_b32_e32 v1, v246, v1, vcc
	v_lshlrev_b32_e32 v107, 2, v1
	v_xor_b32_e32 v1, 8, v246
	v_cmp_lt_i32_e32 vcc, v1, v0
	v_lshl_add_u64 v[54:55], s[2:3], 0, v[8:9]
	v_readlane_b32 s2, v252, 58
	v_cndmask_b32_e32 v1, v246, v1, vcc
	v_lshlrev_b32_e32 v108, 2, v1
	v_xor_b32_e32 v1, 16, v246
	v_cmp_lt_i32_e32 vcc, v1, v0
	v_readlane_b32 s3, v252, 59
	v_readlane_b32 s4, v254, 55
	v_cndmask_b32_e32 v1, v246, v1, vcc
	v_lshlrev_b32_e32 v109, 2, v1
	v_xor_b32_e32 v1, 32, v246
	v_cmp_lt_i32_e32 vcc, v1, v0
	v_readlane_b32 s5, v254, 56
	s_and_b64 s[4:5], s[4:5], exec
	v_cndmask_b32_e32 v0, v246, v1, vcc
	v_lshlrev_b32_e32 v110, 2, v0
	v_lshlrev_b32_e32 v0, 3, v103
	v_mov_b32_e32 v1, v9
	v_lshl_add_u64 v[58:59], s[2:3], 0, v[0:1]
	v_readlane_b32 s2, v254, 34
	v_readlane_b32 s3, v254, 35
	v_readlane_b32 s4, v254, 36
	v_ashrrev_i32_e32 v51, 31, v50
	v_lshl_add_u64 v[68:69], s[2:3], 0, v[8:9]
	v_readlane_b32 s2, v254, 46
	v_readlane_b32 s3, v254, 47
	v_readlane_b32 s5, v254, 37
	v_readlane_b32 s8, v254, 22
	v_lshl_add_u64 v[70:71], s[2:3], 0, v[8:9]
	v_readlane_b32 s2, v252, 32
	v_readlane_b32 s3, v252, 33
	s_cselect_b32 s5, s5, s93
	s_cselect_b32 s4, s4, s92
	v_lshl_add_u64 v[80:81], s[2:3], 0, v[50:51]
	s_nop 0
	v_readfirstlane_b32 s14, v80
.Lrev_n3_loop:
	s_add_u32 s15, s14, s74
	s_cmp_le_u32 s15, 0x207f
	s_cbranch_scc0 .Lrev_n3_done
	s_mov_b32 s14, s15
	s_branch .Lrev_n3_loop
.Lrev_n3_done:
	v_mov_b32_e32 v80, s14
	v_readlane_b32 s9, v254, 23
	v_lshlrev_b64 v[0:1], 13, v[80:81]
	v_readlane_b32 s2, v252, 62
	v_lshl_add_u64 v[52:53], s[8:9], 0, v[8:9]
	v_lshl_add_u64 v[56:57], s[4:5], 0, v[8:9]
	s_mov_b64 s[4:5], 0x1000
	s_mov_b64 s[8:9], 0x1400
	s_mov_b64 s[14:15], 0x1800
	s_mov_b64 s[18:19], 0x1c00
	v_lshl_or_b32 v0, v103, 4, v0
	v_readlane_b32 s3, v252, 63
	v_lshl_add_u64 v[60:61], v[54:55], 0, s[4:5]
	v_lshl_add_u64 v[62:63], v[54:55], 0, s[8:9]
	v_lshl_add_u64 v[64:65], v[54:55], 0, s[14:15]
	v_lshl_add_u64 v[66:67], v[54:55], 0, s[18:19]
	v_lshl_add_u64 v[72:73], v[70:71], 0, s[4:5]
	v_lshl_add_u64 v[74:75], v[70:71], 0, s[8:9]
	v_lshl_add_u64 v[76:77], v[70:71], 0, s[14:15]
	v_lshl_add_u64 v[78:79], v[70:71], 0, s[18:19]
	v_lshl_add_u64 v[82:83], s[2:3], 0, v[0:1]
	s_mov_b64 s[2:3], 0
	global_load_dwordx4 v[136:139], v[54:55], off
	global_load_dwordx4 v[140:143], v[54:55], off offset:1024
	global_load_dwordx4 v[144:147], v[54:55], off offset:2048
	global_load_dwordx4 v[148:151], v[54:55], off offset:3072
	global_load_dwordx4 v[152:155], v[60:61], off
	global_load_dwordx4 v[156:159], v[62:63], off
	global_load_dwordx4 v[160:163], v[64:65], off
	global_load_dwordx4 v[164:167], v[66:67], off
	global_load_dwordx4 v[168:171], v[70:71], off
	global_load_dwordx4 v[172:175], v[70:71], off offset:1024
	global_load_dwordx4 v[176:179], v[70:71], off offset:2048
	global_load_dwordx4 v[180:183], v[70:71], off offset:3072
	global_load_dwordx4 v[184:187], v[72:73], off
	global_load_dwordx4 v[188:191], v[74:75], off
	global_load_dwordx4 v[192:195], v[76:77], off
	global_load_dwordx4 v[204:207], v[78:79], off
	s_branch .LBB0_2099
.LBB0_2098:
	v_subrev_u32_e32 v80, s74, v80
	s_movk_i32 s4, 0x207f
	v_cmp_gt_i32_e32 vcc, 0, v80
	v_readlane_b32 s4, v254, 53
	v_readlane_b32 s5, v254, 54
	s_sub_u32 s4, 0, s4
	s_subb_u32 s5, 0, s5
	s_or_b64 s[2:3], vcc, s[2:3]
	s_nop 0
	v_lshl_add_u64 v[82:83], v[82:83], 0, s[4:5]
	s_andn2_b64 exec, exec, s[2:3]
	s_cbranch_execz .LBB0_2105
